# first phase rmsnorm row loop software-pipelined as well
# baseline (speedup 1.0000x reference)
; __global__ void __launch_bounds__(NWAVES * 64, 2) hymba_fwd(Args args) {
;     ...
;         { f32x4 gv[4];
; #pragma unroll
;           for (int j = 0; j < 4; ++j) gv[j] = *(const f32x4*)(args.in[4] + 4 * lane + 256 * j);
;           for (int m = gw; m < MROWS; m += NGW) { const f32x4* xr = (const f32x4*)xrow_ptr(args, m) + lane; f32x4 v[4]; float s = 0.f;
; #pragma unroll
;             for (int j = 0; j < 4; ++j) { v[j] = __builtin_nontemporal_load(xr + 64 * j); s += (v[j].x * v[j].x + v[j].y * v[j].y) + (v[j].z * v[j].z + v[j].w * v[j].w); }
;             const float rs = 1.0f / sqrtf(wave_sum(s) * (1.0f / DM) + EPS);
.LBB0_43:
	s_or_b64 exec, exec, s[4:5]
	s_load_dwordx16 s[4:19], s[0:1], 0x40
	s_cmp_lt_i32 s80, 0xc000
	v_lshlrev_b32_e32 v147, 2, v128
	s_cbranch_scc0 .LBB0_46
	v_lshlrev_b32_e32 v12, 2, v147
	s_waitcnt lgkmcnt(0)
	global_load_dwordx4 v[0:3], v12, s[44:45]
	global_load_dwordx4 v[4:7], v12, s[44:45] offset:1024
	global_load_dwordx4 v[8:11], v12, s[44:45] offset:2048
	s_nop 0
	global_load_dwordx4 v[12:15], v12, s[44:45] offset:3072
	s_ashr_i32 s81, s80, 31
	s_lshl_b64 s[24:25], s[80:81], 11
	s_add_u32 s24, s70, s24
	v_mov_b32_e32 v19, 0
	v_lshlrev_b32_e32 v18, 3, v128
	s_addc_u32 s25, s71, s25
	s_mov_b64 s[0:1], 0x1900000
	s_ashr_i32 s35, s34, 31
	v_lshl_add_u64 v[18:19], s[24:25], 0, v[18:19]
	v_lshlrev_b32_e32 v17, 4, v128
	v_mov_b32_e32 v22, 0x358637bd
	v_mov_b32_e32 v23, 0x3a800000
	s_mov_b32 s28, 0xf800000
	v_mov_b32_e32 v24, 0x260
	s_movk_i32 s29, 0x7fff
	v_mov_b32_e32 v25, 1
	s_lshl_b64 s[24:25], s[34:35], 11
	v_lshl_add_u64 v[18:19], v[18:19], 0, s[0:1]
	s_mov_b64 s[26:27], s[80:81]
	s_waitcnt vmcnt(3)
	v_mov_b32_e32 v20, v1
	v_mov_b32_e32 v21, v3
	v_mov_b32_e32 v1, v2
	s_waitcnt vmcnt(2)
	v_mov_b32_e32 v2, v5
	v_mov_b32_e32 v3, v7
	v_mov_b32_e32 v5, v6
	s_waitcnt vmcnt(1)
	v_mov_b32_e32 v6, v9
	v_mov_b32_e32 v7, v11
	v_mov_b32_e32 v9, v10
	s_waitcnt vmcnt(0)
	v_mov_b32_e32 v10, v13
	v_mov_b32_e32 v11, v15
	v_mov_b32_e32 v13, v14
	s_add_i32 s0, s26, 0xffff8000
	s_cmp_lt_i32 s26, 0x8000
	s_cselect_b32 s1, s27, 0
	s_cselect_b32 s0, s26, s0
	s_cselect_b32 s30, s37, s39
	s_cselect_b32 s31, s36, s38
	s_lshl_b64 s[0:1], s[0:1], 12
	s_add_u32 s0, s31, s0
	s_addc_u32 s1, s30, s1
	global_load_dwordx4 v[26:29], v17, s[0:1] nt
	global_load_dwordx4 v[30:33], v17, s[0:1] offset:1024 nt
	global_load_dwordx4 v[34:37], v17, s[0:1] offset:2048 nt
	global_load_dwordx4 v[38:41], v17, s[0:1] offset:3072 nt
	s_add_u32 s26, s26, s34
	s_addc_u32 s27, s27, s35
	s_waitcnt vmcnt(0)
.LBB0_45:
	s_cmp_gt_i32 s26, 0xbfff
	s_cselect_b32 s98, 1, 0
	s_cbranch_scc1 .Lp0_nopf
	s_add_i32 s0, s26, 0xffff8000
	s_cmp_lt_i32 s26, 0x8000
	s_cselect_b32 s1, s27, 0
	s_cselect_b32 s0, s26, s0
	s_cselect_b32 s30, s37, s39
	s_cselect_b32 s31, s36, s38
	s_lshl_b64 s[0:1], s[0:1], 12
	s_add_u32 s0, s31, s0
	s_addc_u32 s1, s30, s1
	global_load_dwordx4 v[64:67], v17, s[0:1] nt
	global_load_dwordx4 v[68:71], v17, s[0:1] offset:1024 nt
	global_load_dwordx4 v[72:75], v17, s[0:1] offset:2048 nt
	global_load_dwordx4 v[76:79], v17, s[0:1] offset:3072 nt
	s_add_u32 s26, s26, s34
	s_addc_u32 s27, s27, s35
.Lp0_nopf:
	v_mov_b32_e32 v48, 0
	v_mov_b32_e32 v49, 0
	v_mul_f32_e32 v50, v27, v27
	v_mul_f32_e32 v51, v29, v29
	v_mul_f32_e32 v52, v31, v31
	v_mul_f32_e32 v53, v33, v33
	v_mul_f32_e32 v54, v35, v35
	v_mul_f32_e32 v55, v37, v37
	v_fmac_f32_e32 v50, v26, v26
	v_fmac_f32_e32 v51, v28, v28
	v_fmac_f32_e32 v52, v30, v30
	v_fmac_f32_e32 v53, v32, v32
	v_mul_f32_e32 v56, v39, v39
	v_mul_f32_e32 v57, v41, v41
	v_mov_b32_e32 v14, v26
	v_mov_b32_e32 v15, v28
	v_fmac_f32_e32 v54, v34, v34
	v_fmac_f32_e32 v55, v36, v36
	v_mov_b32_e32 v28, v27
	v_add_f32_e32 v26, v50, v51
	v_add_f32_e32 v27, v52, v53
	v_mov_b32_e32 v42, v30
	v_fmac_f32_e32 v56, v38, v38
	v_fmac_f32_e32 v57, v40, v40
	v_add_f32_e32 v30, v54, v55
	v_add_f32_e32 v26, v26, v27
	v_mov_b32_e32 v43, v32
	v_mov_b32_e32 v32, v31
	v_add_f32_e32 v31, v56, v57
	v_add_f32_e32 v26, v26, v30
	v_add_f32_e32 v26, v26, v31
	v_mov_b32_e32 v44, v34
	v_mov_b32_e32 v45, v36
	v_add_f32_dpp v26, v26, v26 quad_perm:[1,0,3,2] row_mask:0xf bank_mask:0xf bound_ctrl:1
	v_mov_b32_e32 v36, v35
	v_mov_b32_e32 v46, v38
	v_add_f32_dpp v26, v26, v26 quad_perm:[2,3,0,1] row_mask:0xf bank_mask:0xf bound_ctrl:1
	v_mov_b32_e32 v47, v40
	v_mov_b32_e32 v40, v39
	v_add_f32_dpp v26, v26, v26 row_half_mirror row_mask:0xf bank_mask:0xf bound_ctrl:1
	s_nop 1
	v_add_f32_dpp v26, v26, v26 row_mirror row_mask:0xf bank_mask:0xf bound_ctrl:1
	s_nop 1
	v_mov_b32_dpp v48, v26 row_bcast:15 row_mask:0xa bank_mask:0xf
	v_add_f32_e32 v26, v26, v48
	s_nop 1
	v_mov_b32_dpp v49, v26 row_bcast:31 row_mask:0xc bank_mask:0xf
	v_add_f32_e32 v26, v26, v49
	s_nop 0
	v_readlane_b32 s0, v26, 63
	s_nop 1
	v_fma_f32 v26, s0, v23, v22
	v_mul_f32_e32 v27, 0x4f800000, v26
	v_cmp_gt_f32_e32 vcc, s28, v26
	s_nop 1
	v_cndmask_b32_e32 v26, v26, v27, vcc
	v_sqrt_f32_e32 v27, v26
	s_nop 0
	v_add_u32_e32 v30, -1, v27
	v_add_u32_e32 v31, 1, v27
	v_fma_f32 v34, -v30, v27, v26
	v_fma_f32 v35, -v31, v27, v26
	v_cmp_ge_f32_e64 s[0:1], 0, v34
	s_nop 1
	v_cndmask_b32_e64 v27, v27, v30, s[0:1]
	v_cmp_lt_f32_e64 s[0:1], 0, v35
	s_nop 1
	v_cndmask_b32_e64 v27, v27, v31, s[0:1]
	v_mul_f32_e32 v30, 0x37800000, v27
	v_cndmask_b32_e32 v27, v27, v30, vcc
	v_cmp_class_f32_e32 vcc, v26, v24
	s_nop 1
	v_cndmask_b32_e32 v26, v27, v26, vcc
	v_div_scale_f32 v27, s[0:1], v26, v26, 1.0
	v_rcp_f32_e32 v31, v27
; __device__ __forceinline__ unsigned f2bf(float f) { unsigned u = __builtin_bit_cast(unsigned, f); return (u + 0x7fffu + ((u >> 16) & 1u)) >> 16; }
; __device__ __forceinline__ unsigned pk2(float lo, float hi) { return f2bf(lo) | (f2bf(hi) << 16); }
; __global__ void __launch_bounds__(NWAVES * 64, 2) hymba_fwd(Args args) {
;     ...
;             const float rs = 1.0f / sqrtf(wave_sum(s) * (1.0f / DM) + EPS);
;             v2u* o8 = (v2u*)(H + (size_t)m * DM) + lane;
; #pragma unroll
;             for (int j = 0; j < 4; ++j) { v2u w; w.x = pk2(v[j].x * rs * gv[j].x, v[j].y * rs * gv[j].y); w.y = pk2(v[j].z * rs * gv[j].z, v[j].w * rs * gv[j].w); o8[64 * j] = w; } } }
	v_div_scale_f32 v30, vcc, 1.0, v26, 1.0
	v_fma_f32 v34, -v27, v31, 1.0
	v_fmac_f32_e32 v31, v34, v31
	v_mul_f32_e32 v34, v30, v31
	v_fma_f32 v35, -v27, v34, v30
	v_fmac_f32_e32 v34, v35, v31
	v_fma_f32 v27, -v27, v34, v30
	v_div_fmas_f32 v27, v27, v31, v34
	v_div_fixup_f32 v26, v27, v26, 1.0
	v_pk_mul_f32 v[28:29], v[26:27], v[28:29] op_sel_hi:[0,1]
	v_pk_mul_f32 v[14:15], v[26:27], v[14:15] op_sel_hi:[0,1]
	v_pk_mul_f32 v[30:31], v[26:27], v[42:43] op_sel_hi:[0,1]
	v_pk_mul_f32 v[32:33], v[26:27], v[32:33] op_sel_hi:[0,1]
	v_pk_mul_f32 v[34:35], v[26:27], v[44:45] op_sel_hi:[0,1]
	v_pk_mul_f32 v[36:37], v[26:27], v[36:37] op_sel_hi:[0,1]
	v_pk_mul_f32 v[38:39], v[26:27], v[46:47] op_sel_hi:[0,1]
	v_pk_mul_f32 v[26:27], v[26:27], v[40:41] op_sel_hi:[0,1]
	v_pk_mul_f32 v[28:29], v[28:29], v[20:21]
	v_pk_mul_f32 v[14:15], v[14:15], v[0:1]
	v_pk_mul_f32 v[32:33], v[32:33], v[2:3]
	v_pk_mul_f32 v[36:37], v[36:37], v[6:7]
	v_pk_mul_f32 v[26:27], v[26:27], v[10:11]
	v_and_b32_sdwa v42, v29, v25 dst_sel:DWORD dst_unused:UNUSED_PAD src0_sel:WORD_1 src1_sel:DWORD
	v_and_b32_sdwa v43, v28, v25 dst_sel:DWORD dst_unused:UNUSED_PAD src0_sel:WORD_1 src1_sel:DWORD
	v_pk_mul_f32 v[30:31], v[30:31], v[4:5]
	v_pk_mul_f32 v[34:35], v[34:35], v[8:9]
	v_pk_mul_f32 v[38:39], v[38:39], v[12:13]
	v_and_b32_sdwa v40, v15, v25 dst_sel:DWORD dst_unused:UNUSED_PAD src0_sel:WORD_1 src1_sel:DWORD
	v_and_b32_sdwa v41, v14, v25 dst_sel:DWORD dst_unused:UNUSED_PAD src0_sel:WORD_1 src1_sel:DWORD
	v_and_b32_sdwa v46, v33, v25 dst_sel:DWORD dst_unused:UNUSED_PAD src0_sel:WORD_1 src1_sel:DWORD
	v_and_b32_sdwa v47, v32, v25 dst_sel:DWORD dst_unused:UNUSED_PAD src0_sel:WORD_1 src1_sel:DWORD
	v_and_b32_sdwa v50, v37, v25 dst_sel:DWORD dst_unused:UNUSED_PAD src0_sel:WORD_1 src1_sel:DWORD
	v_and_b32_sdwa v51, v36, v25 dst_sel:DWORD dst_unused:UNUSED_PAD src0_sel:WORD_1 src1_sel:DWORD
	v_and_b32_sdwa v54, v27, v25 dst_sel:DWORD dst_unused:UNUSED_PAD src0_sel:WORD_1 src1_sel:DWORD
	v_and_b32_sdwa v55, v26, v25 dst_sel:DWORD dst_unused:UNUSED_PAD src0_sel:WORD_1 src1_sel:DWORD
	v_add3_u32 v29, v29, v42, s29
	v_add3_u32 v28, v28, v43, s29
	v_and_b32_sdwa v44, v31, v25 dst_sel:DWORD dst_unused:UNUSED_PAD src0_sel:WORD_1 src1_sel:DWORD
	v_and_b32_sdwa v45, v30, v25 dst_sel:DWORD dst_unused:UNUSED_PAD src0_sel:WORD_1 src1_sel:DWORD
	v_and_b32_sdwa v48, v35, v25 dst_sel:DWORD dst_unused:UNUSED_PAD src0_sel:WORD_1 src1_sel:DWORD
	v_and_b32_sdwa v49, v34, v25 dst_sel:DWORD dst_unused:UNUSED_PAD src0_sel:WORD_1 src1_sel:DWORD
	v_and_b32_sdwa v52, v39, v25 dst_sel:DWORD dst_unused:UNUSED_PAD src0_sel:WORD_1 src1_sel:DWORD
	v_and_b32_sdwa v53, v38, v25 dst_sel:DWORD dst_unused:UNUSED_PAD src0_sel:WORD_1 src1_sel:DWORD
	v_add3_u32 v14, v14, v41, s29
	v_add3_u32 v15, v15, v40, s29
	v_add3_u32 v33, v33, v46, s29
	v_add3_u32 v32, v32, v47, s29
	v_add3_u32 v37, v37, v50, s29
	v_add3_u32 v36, v36, v51, s29
	v_add3_u32 v27, v27, v54, s29
	v_add3_u32 v26, v26, v55, s29
	v_and_b32_e32 v29, 0xffff0000, v29
	v_and_b32_e32 v28, 0xffff0000, v28
	v_add3_u32 v30, v30, v45, s29
	v_add3_u32 v31, v31, v44, s29
	v_add3_u32 v34, v34, v49, s29
	v_add3_u32 v35, v35, v48, s29
	v_add3_u32 v38, v38, v53, s29
	v_add3_u32 v39, v39, v52, s29
	v_and_b32_e32 v33, 0xffff0000, v33
	v_and_b32_e32 v32, 0xffff0000, v32
	v_and_b32_e32 v37, 0xffff0000, v37
	v_and_b32_e32 v36, 0xffff0000, v36
	v_and_b32_e32 v40, 0xffff0000, v27
	v_and_b32_e32 v41, 0xffff0000, v26
	v_or_b32_sdwa v15, v29, v15 dst_sel:DWORD dst_unused:UNUSED_PAD src0_sel:DWORD src1_sel:WORD_1
	v_or_b32_sdwa v14, v28, v14 dst_sel:DWORD dst_unused:UNUSED_PAD src0_sel:DWORD src1_sel:WORD_1
	v_or_b32_sdwa v27, v33, v31 dst_sel:DWORD dst_unused:UNUSED_PAD src0_sel:DWORD src1_sel:WORD_1
	v_or_b32_sdwa v26, v32, v30 dst_sel:DWORD dst_unused:UNUSED_PAD src0_sel:DWORD src1_sel:WORD_1
	v_or_b32_sdwa v29, v37, v35 dst_sel:DWORD dst_unused:UNUSED_PAD src0_sel:DWORD src1_sel:WORD_1
	v_or_b32_sdwa v28, v36, v34 dst_sel:DWORD dst_unused:UNUSED_PAD src0_sel:DWORD src1_sel:WORD_1
	v_or_b32_sdwa v31, v40, v39 dst_sel:DWORD dst_unused:UNUSED_PAD src0_sel:DWORD src1_sel:WORD_1
	v_or_b32_sdwa v30, v41, v38 dst_sel:DWORD dst_unused:UNUSED_PAD src0_sel:DWORD src1_sel:WORD_1
	global_store_dwordx2 v[18:19], v[14:15], off
	global_store_dwordx2 v[18:19], v[26:27], off offset:512
	global_store_dwordx2 v[18:19], v[28:29], off offset:1024
	global_store_dwordx2 v[18:19], v[30:31], off offset:1536
	v_lshl_add_u64 v[18:19], v[18:19], 0, s[24:25]
	s_cmp_lg_u32 s98, 0
	s_cbranch_scc1 .LBB0_46
	s_waitcnt vmcnt(4)
	s_nop 0
	v_mov_b64_e32 v[26:27], v[64:65]
	v_mov_b64_e32 v[28:29], v[66:67]
	v_mov_b64_e32 v[30:31], v[68:69]
	v_mov_b64_e32 v[32:33], v[70:71]
	v_mov_b64_e32 v[34:35], v[72:73]
	v_mov_b64_e32 v[36:37], v[74:75]
	v_mov_b64_e32 v[38:39], v[76:77]
	v_mov_b64_e32 v[40:41], v[78:79]
	s_branch .LBB0_45
